# skip the initial cooperative-groups grid.sync (first data seam already uses the XCD barrier with its own census rendezvous)
# baseline (speedup 1.0000x reference)
.LBB0_3:
	s_or_b64 exec, exec, s[0:1]
	s_waitcnt lgkmcnt(0)
	s_sub_i32 s0, s59, s58
	s_cmp_lt_i32 s0, 2
	s_barrier
	s_branch .LBB0_15
	v_lshrrev_b32_e32 v2, 20, v0
	v_lshrrev_b32_e32 v0, 10, v0
	v_or_b32_e32 v0, v0, v2
	s_movk_i32 s0, 0x3ff
	v_and_or_b32 v0, v0, s0, v1
	v_cmp_eq_u32_e32 vcc, 0, v0
	s_barrier
	s_and_saveexec_b64 s[0:1], vcc
	s_cbranch_execz .LBB0_14
	buffer_wbl2 sc1
	s_waitcnt vmcnt(0)
	s_load_dwordx2 s[4:5], s[4:5], 0x58
	v_mov_b32_e32 v2, 0
	s_mov_b64 s[6:7], exec
	v_mbcnt_lo_u32_b32 v1, s6, 0
	v_mbcnt_hi_u32_b32 v1, s7, v1
	s_waitcnt lgkmcnt(0)
	global_load_dword v0, v2, s[4:5] offset:40
	v_cmp_eq_u32_e32 vcc, 0, v1
	s_and_saveexec_b64 s[8:9], vcc
	s_cbranch_execz .LBB0_7
	s_bcnt1_i32_b64 s6, s[6:7]
	v_mov_b32_e32 v3, s6
	global_atomic_add v3, v2, v3, s[4:5] offset:32 sc0
